# plus scan next-chunk loads via SGPR bases and last-chunk copies off main path
# baseline (speedup 1.0000x reference)
; #define LAS __attribute__((address_space(3)))
; template <class RecFn>
; __device__ __forceinline__ void gdn_scan(LAS unsigned char* lds, int bh, int b0, RecFn rec_of, const float* gtarr, bf16_t* zb, const float* gnorm_w, float* Sout, const unsigned* late_cnt, unsigned late_need, int cwait) {
;     ...
;         if (c + 1 < NCHUNK) {
;             const unsigned char* rec = rec_of((bl * NCHUNK + c + 1) * 8 + h); LAS unsigned char* nb = lds + P3_BUF + ((c + 1) & 1) * REC_DMA;
; #pragma unroll
;             for (int pz = 0; pz < 7; ++pz) { const int piece = wave + 8 * pz; __builtin_amdgcn_global_load_lds((const unsigned*)(rec + piece * 1024 + lane * 16), (LAS unsigned*)(nb + piece * 1024), 16, 0, 0); }
; #pragma unroll
;             for (int rt = 0; rt < 4; ++rt) Un[rt] = *(const u32x2*)(rec + REC_U + ((rt * 8 + wave) * 64 + lane) * 8);
;             gtn = gtarr[(bl * NCHUNK + c + 1) * 8 + h];
;             { const int t = 64 * (c + 1) - 48 + zi; const bf16_t* zr = zb + (size_t)(b * LP + t) * D + h * 128 + 16 * zseg; zn0 = *(const u32x4*)zr; zn1 = *(const u32x4*)(zr + 8); }
;         }
.LBB0_780:
	s_cmp_eq_u32 s31, 32
	s_cbranch_scc1 .Lsc_last
	s_add_i32 s22, s31, s17
	s_lshl_b32 s22, s22, 3
	s_add_i32 s22, s22, s28
	s_add_i32 s24, s22, 0xfffff9c8
	s_ashr_i32 s23, s22, 31
	s_cmpk_lt_i32 s22, 0x638
	s_cselect_b32 s24, s22, s24
	s_cselect_b32 s25, s23, 0
	s_mul_i32 s25, s25, 0x12000
	s_mul_hi_u32 s36, s24, 0x12000
	s_cselect_b32 s34, s64, s49
	s_cselect_b32 s35, s33, s48
	s_add_i32 s36, s36, s25
	s_mul_i32 s24, s24, 0x12000
	s_add_u32 s24, s35, s24
	s_addc_u32 s25, s34, s36
	s_bitcmp1_b32 s30, 0
	s_cselect_b32 s34, 0xe000, 0
	s_add_i32 s34, s26, s34
	s_mov_b32 m0, s34
	s_add_u32 s98, s24, s0
	s_addc_u32 s99, s25, s1
	global_load_lds_dwordx4 v60, s[98:99]
	s_add_i32 m0, s34, 0x2000
	s_add_u32 s100, s24, s4
	s_addc_u32 s101, s25, s5
	global_load_lds_dwordx4 v60, s[100:101]
	s_add_i32 m0, s34, 0x4000
	s_add_u32 s98, s24, s6
	s_addc_u32 s99, s25, s7
	global_load_lds_dwordx4 v60, s[98:99]
	s_add_i32 m0, s34, 0x6000
	s_add_u32 s100, s24, s8
	s_addc_u32 s101, s25, s9
	global_load_lds_dwordx4 v60, s[100:101]
	s_add_i32 m0, s34, 0x8000
	s_add_u32 s98, s24, s12
	s_addc_u32 s99, s25, s13
	global_load_lds_dwordx4 v60, s[98:99]
	s_add_i32 m0, s34, 0xa000
	s_add_u32 s100, s24, s18
	s_addc_u32 s101, s25, s19
	global_load_lds_dwordx4 v60, s[100:101]
	s_add_i32 m0, s34, 0xc000
	s_add_u32 s98, s24, s20
	s_addc_u32 s99, s25, s21
	global_load_lds_dwordx4 v60, s[98:99]
	s_add_u32 s24, s24, 0xe000
	s_addc_u32 s25, s25, 0
	global_load_dwordx2 v[88:89], v66, s[24:25]
	global_load_dwordx2 v[90:91], v68, s[24:25]
	global_load_dwordx2 v[92:93], v70, s[24:25]
	global_load_dwordx2 v[94:95], v72, s[24:25]
	v_lshl_add_u32 v44, s30, 6, v114
	s_lshl_b64 s[22:23], s[22:23], 2
	v_ashrrev_i32_e32 v45, 31, v44
	s_add_u32 s22, s58, s22
	v_lshlrev_b64 v[44:45], 11, v[44:45]
	s_addc_u32 s23, s57, s23
	v_lshl_add_u64 v[48:49], v[74:75], 0, v[44:45]
	global_load_dword v34, v35, s[22:23]
	global_load_dwordx4 v[44:47], v[48:49], off offset:16
	s_nop 0
	global_load_dwordx4 v[48:51], v[48:49], off

; template <class RecFn>
; __device__ __forceinline__ void gdn_scan(LAS unsigned char* lds, int bh, int b0, RecFn rec_of, const float* gtarr, bf16_t* zb, const float* gnorm_w, float* Sout, const unsigned* late_cnt, unsigned late_need, int cwait) {
;     ...
;         u32x2 Uc[4];
; #pragma unroll
;         for (int rt = 0; rt < 4; ++rt) Uc[rt] = Un[rt];
;         const float gt = gtn;
;         const u32x4 zf0 = zp0, zf1 = zp1;
;         zp0 = zn0; zp1 = zn1;
.Lsc_last:
	v_mov_b64_e32 v[46:47], v[38:39]
	v_mov_b64_e32 v[50:51], v[42:43]
	v_mov_b64_e32 v[88:89], v[86:87]
	v_mov_b64_e32 v[90:91], v[84:85]
	v_mov_b64_e32 v[92:93], v[82:83]
	v_mov_b64_e32 v[94:95], v[80:81]
	v_mov_b64_e32 v[44:45], v[36:37]
	v_mov_b64_e32 v[48:49], v[40:41]
	v_mov_b32_e32 v34, v76
	s_branch .LBB0_782
